# sample item score loop: key rows of steps 1..3 requested together with step 0 (fresh registers), waits counted down 6/4/2/0
# speedup vs baseline: 1.0014x; 1.0014x over previous
; #define LAS __attribute__((address_space(3)))
; __device__ __forceinline__ float dot4(f32x4 a, f32x4 b) { return (a[0] * b[0] + a[1] * b[1]) + (a[2] * b[2] + a[3] * b[3]); }
; __device__ __forceinline__ float grp16_sum(float v) { return sum16(v); }
; __device__ __forceinline__ void attn_sample_item(const SmpArgs& a, int b, int g, LAS unsigned char* lds, int tid) {
;     ...
;     f32x4 qv[4];
; #pragma unroll
;     for (int h = 0; h < 4; ++h) qv[h] = *(const LAS f32x4*)(qn + h * 64 + 4 * d4);
;     const float* pqk = a.PQ + ((size_t)(b * 4 + g) * 128) * 256 + 4 * d4;
;     const float* pqv = a.PQ + ((size_t)((NSMP + b) * 4 + g) * 128) * 256 + 4 * d4;
;     { const f32x4 cbk = *(const f32x4*)(a.CB + 4 * d4);
; #pragma unroll
;       for (int it = 0; it < 4; ++it) { const int c = 16 * w + 4 * it + kq; const int cc = c < 127 ? c : 126;
;           const f32x4 kx = *(const f32x4*)(pqk + (size_t)cc * 256) + *(const f32x4*)(pqk + (size_t)(cc + 1) * 256 + 64) + cbk;
; #pragma unroll
;           for (int h = 0; h < 4; ++h) { const float s = grp16_sum(dot4(kx, qv[h])); if (d4 == 0) sc[h * 128 + c] = c < 127 ? s : -1e30f; } } }
.LBB0_2508:
	s_or_b64 exec, exec, s[0:1]
	s_ashr_i32 s85, s84, 31
	s_lshl_b64 s[0:1], s[84:85], 17
	v_and_b32_e32 v54, 15, v0
	s_add_u32 s0, s74, s0
	v_ashrrev_i32_e32 v49, 6, v0
	v_lshrrev_b32_e32 v56, 4, v17
	v_lshlrev_b32_e32 v14, 4, v54
	s_addc_u32 s1, s75, s1
	v_mov_b32_e32 v15, v1
	v_lshl_add_u64 v[52:53], s[0:1], 0, v[14:15]
	v_lshl_or_b32 v15, v49, 4, v56
	v_cmp_gt_i32_e64 s[10:11], s34, v15
	s_waitcnt vmcnt(4)
	v_add_u32_e32 v2, 0, v14
	v_add_u32_e32 v2, 0x21200, v2
	v_cndmask_b32_e64 v26, v228, v15, s[10:11]
	v_ashrrev_i32_e32 v27, 31, v26
	v_lshlrev_b64 v[28:29], 10, v[26:27]
	v_lshl_add_u64 v[30:31], v[52:53], 0, v[28:29]
	s_waitcnt lgkmcnt(0)
	s_barrier
	ds_read_b128 v[18:21], v2
	ds_read_b128 v[10:13], v2 offset:256
	ds_read_b128 v[6:9], v2 offset:512
	ds_read_b128 v[2:5], v2 offset:768
	global_load_dwordx4 v[22:25], v14, s[44:45]
	global_load_dwordx4 v[32:35], v[30:31], off
	v_lshl_add_u64 v[30:31], v[28:29], 0, s[78:79]
	v_lshl_add_u64 v[36:37], v[52:53], 0, v[30:31]
	global_load_dwordx4 v[36:39], v[36:37], off offset:256
	v_or_b32_e32 v104, 4, v15
	v_cmp_gt_i32_e64 s[98:99], s34, v104
	s_nop 1
	v_cndmask_b32_e64 v106, v228, v104, s[98:99]
	v_ashrrev_i32_e32 v107, 31, v106
	v_lshlrev_b64 v[106:107], 10, v[106:107]
	v_lshl_add_u64 v[108:109], v[52:53], 0, v[106:107]
	v_lshl_add_u64 v[106:107], v[106:107], 0, s[78:79]
	v_lshl_add_u64 v[106:107], v[52:53], 0, v[106:107]
	global_load_dwordx4 v[80:83], v[108:109], off
	global_load_dwordx4 v[84:87], v[106:107], off offset:256
	v_or_b32_e32 v110, 8, v15
	v_cmp_gt_i32_e64 s[100:101], s34, v110
	s_nop 1
	v_cndmask_b32_e64 v112, v228, v110, s[100:101]
	v_ashrrev_i32_e32 v113, 31, v112
	v_lshlrev_b64 v[112:113], 10, v[112:113]
	v_lshl_add_u64 v[114:115], v[52:53], 0, v[112:113]
	v_lshl_add_u64 v[112:113], v[112:113], 0, s[78:79]
	v_lshl_add_u64 v[112:113], v[52:53], 0, v[112:113]
	global_load_dwordx4 v[88:91], v[114:115], off
	global_load_dwordx4 v[92:95], v[112:113], off offset:256
	v_or_b32_e32 v126, 12, v15
	v_cmp_gt_i32_e64 s[98:99], s34, v126
	s_nop 1
	v_cndmask_b32_e64 v128, v228, v126, s[98:99]
	v_ashrrev_i32_e32 v129, 31, v128
	v_lshlrev_b64 v[128:129], 10, v[128:129]
	v_lshl_add_u64 v[130:131], v[52:53], 0, v[128:129]
	v_lshl_add_u64 v[128:129], v[128:129], 0, s[78:79]
	v_lshl_add_u64 v[128:129], v[52:53], 0, v[128:129]
	global_load_dwordx4 v[96:99], v[130:131], off
	global_load_dwordx4 v[100:103], v[128:129], off offset:256
	v_cmp_eq_u32_e64 s[8:9], 0, v54
	v_lshl_add_u32 v27, v15, 2, s35
	s_waitcnt vmcnt(6)
	v_pk_add_f32 v[34:35], v[34:35], v[38:39]
	v_pk_add_f32 v[36:37], v[32:33], v[36:37]
	v_pk_add_f32 v[32:33], v[24:25], v[34:35]
	v_pk_add_f32 v[34:35], v[22:23], v[36:37]
	s_waitcnt lgkmcnt(3)
	v_mul_f32_e32 v37, v21, v33
	v_mul_f32_e32 v36, v19, v35
	v_fmac_f32_e32 v36, v18, v34
	v_fmac_f32_e32 v37, v20, v32
	v_add_f32_e32 v36, v36, v37
	s_nop 1
	v_add_f32_dpp v36, v36, v36 quad_perm:[1,0,3,2] row_mask:0xf bank_mask:0xf bound_ctrl:1
	s_nop 1
	v_add_f32_dpp v36, v36, v36 quad_perm:[2,3,0,1] row_mask:0xf bank_mask:0xf bound_ctrl:1
	s_nop 1
	v_add_f32_dpp v36, v36, v36 row_half_mirror row_mask:0xf bank_mask:0xf bound_ctrl:1
	s_nop 1
	v_mov_b32_dpp v37, v36 row_mirror row_mask:0xf bank_mask:0xf bound_ctrl:1
	s_and_saveexec_b64 s[0:1], s[8:9]
	v_add_f32_e32 v36, v36, v37
	v_cndmask_b32_e64 v36, v229, v36, s[10:11]
	ds_write_b32 v27, v36
	s_or_b64 exec, exec, s[0:1]
	s_waitcnt lgkmcnt(2)
	v_mul_f32_e32 v36, v11, v35
	v_mul_f32_e32 v37, v13, v33
	v_fmac_f32_e32 v36, v10, v34
	v_fmac_f32_e32 v37, v12, v32
	v_add_f32_e32 v36, v36, v37
	s_nop 1
	v_add_f32_dpp v36, v36, v36 quad_perm:[1,0,3,2] row_mask:0xf bank_mask:0xf bound_ctrl:1
	s_nop 1
	v_add_f32_dpp v36, v36, v36 quad_perm:[2,3,0,1] row_mask:0xf bank_mask:0xf bound_ctrl:1
	s_nop 1
	v_add_f32_dpp v36, v36, v36 row_half_mirror row_mask:0xf bank_mask:0xf bound_ctrl:1
	s_nop 1
	v_mov_b32_dpp v37, v36 row_mirror row_mask:0xf bank_mask:0xf bound_ctrl:1
	s_and_saveexec_b64 s[0:1], s[8:9]
	v_add_f32_e32 v36, v36, v37
	v_cndmask_b32_e64 v36, v229, v36, s[10:11]
	ds_write_b32 v27, v36 offset:512
	s_or_b64 exec, exec, s[0:1]
	s_waitcnt lgkmcnt(1)
	v_mul_f32_e32 v36, v7, v35
	v_mul_f32_e32 v37, v9, v33
	v_fmac_f32_e32 v36, v6, v34
	v_fmac_f32_e32 v37, v8, v32
	v_add_f32_e32 v36, v36, v37
	s_nop 1
	v_add_f32_dpp v36, v36, v36 quad_perm:[1,0,3,2] row_mask:0xf bank_mask:0xf bound_ctrl:1
	s_nop 1
	v_add_f32_dpp v36, v36, v36 quad_perm:[2,3,0,1] row_mask:0xf bank_mask:0xf bound_ctrl:1
	s_nop 1
	v_add_f32_dpp v36, v36, v36 row_half_mirror row_mask:0xf bank_mask:0xf bound_ctrl:1
	s_nop 1
	v_mov_b32_dpp v37, v36 row_mirror row_mask:0xf bank_mask:0xf bound_ctrl:1
	s_and_saveexec_b64 s[0:1], s[8:9]
	v_add_f32_e32 v36, v36, v37
	v_cndmask_b32_e64 v36, v229, v36, s[10:11]
	ds_write_b32 v27, v36 offset:1024
	s_or_b64 exec, exec, s[0:1]
	s_waitcnt lgkmcnt(0)
	v_mul_f32_e32 v35, v3, v35
	v_mul_f32_e32 v33, v5, v33
	v_fmac_f32_e32 v35, v2, v34
	v_fmac_f32_e32 v33, v4, v32
	v_add_f32_e32 v32, v35, v33
	s_nop 1
	v_add_f32_dpp v32, v32, v32 quad_perm:[1,0,3,2] row_mask:0xf bank_mask:0xf bound_ctrl:1
	s_nop 1
	v_add_f32_dpp v32, v32, v32 quad_perm:[2,3,0,1] row_mask:0xf bank_mask:0xf bound_ctrl:1
	s_nop 1
	v_add_f32_dpp v32, v32, v32 row_half_mirror row_mask:0xf bank_mask:0xf bound_ctrl:1
	s_nop 1
	v_mov_b32_dpp v33, v32 row_mirror row_mask:0xf bank_mask:0xf bound_ctrl:1
	s_and_saveexec_b64 s[0:1], s[8:9]
	v_add_f32_e32 v32, v32, v33
	v_cndmask_b32_e64 v32, v229, v32, s[10:11]
	ds_write_b32 v27, v32 offset:1536
	s_or_b64 exec, exec, s[0:1]
	v_or_b32_e32 v27, 4, v15
	v_cmp_gt_i32_e64 s[12:13], s34, v27
	s_nop 1
	v_cndmask_b32_e64 v32, v228, v27, s[12:13]
	v_ashrrev_i32_e32 v33, 31, v32
	v_lshlrev_b64 v[34:35], 10, v[32:33]
	v_lshl_add_u64 v[36:37], v[34:35], 0, s[78:79]
	v_lshl_add_u64 v[38:39], v[52:53], 0, v[34:35]
	v_lshl_add_u64 v[42:43], v[52:53], 0, v[36:37]
	v_lshl_add_u32 v27, v27, 2, s35
	s_waitcnt vmcnt(4)
; __device__ __forceinline__ float dot4(f32x4 a, f32x4 b) { return (a[0] * b[0] + a[1] * b[1]) + (a[2] * b[2] + a[3] * b[3]); }
; __device__ __forceinline__ float grp16_sum(float v) { return sum16(v); }
; __device__ __forceinline__ void attn_sample_item(const SmpArgs& a, int b, int g, LAS unsigned char* lds, int tid) {
;     ...
;       for (int it = 0; it < 4; ++it) { const int c = 16 * w + 4 * it + kq; const int cc = c < 127 ? c : 126;
;           const f32x4 kx = *(const f32x4*)(pqk + (size_t)cc * 256) + *(const f32x4*)(pqk + (size_t)(cc + 1) * 256 + 64) + cbk;
; #pragma unroll
;           for (int h = 0; h < 4; ++h) { const float s = grp16_sum(dot4(kx, qv[h])); if (d4 == 0) sc[h * 128 + c] = c < 127 ? s : -1e30f; } } }
	v_mov_b64 v[38:39], v[80:81]
	v_mov_b64 v[40:41], v[82:83]
	v_mov_b64 v[42:43], v[84:85]
	v_mov_b64 v[44:45], v[86:87]
	v_pk_add_f32 v[40:41], v[40:41], v[44:45]
	v_pk_add_f32 v[42:43], v[38:39], v[42:43]
	v_pk_add_f32 v[38:39], v[24:25], v[40:41]
	v_pk_add_f32 v[40:41], v[22:23], v[42:43]
	v_mul_f32_e32 v42, v21, v39
	v_mul_f32_e32 v33, v19, v41
	v_fmac_f32_e32 v33, v18, v40
	v_fmac_f32_e32 v42, v20, v38
	v_add_f32_e32 v33, v33, v42
	s_nop 1
	v_add_f32_dpp v33, v33, v33 quad_perm:[1,0,3,2] row_mask:0xf bank_mask:0xf bound_ctrl:1
	s_nop 1
	v_add_f32_dpp v33, v33, v33 quad_perm:[2,3,0,1] row_mask:0xf bank_mask:0xf bound_ctrl:1
	s_nop 1
	v_add_f32_dpp v33, v33, v33 row_half_mirror row_mask:0xf bank_mask:0xf bound_ctrl:1
	s_nop 1
	v_mov_b32_dpp v42, v33 row_mirror row_mask:0xf bank_mask:0xf bound_ctrl:1
	s_and_saveexec_b64 s[0:1], s[8:9]
	v_add_f32_e32 v33, v33, v42
	v_cndmask_b32_e64 v33, v229, v33, s[12:13]
	ds_write_b32 v27, v33
	s_or_b64 exec, exec, s[0:1]
	v_mul_f32_e32 v33, v11, v41
	v_mul_f32_e32 v42, v13, v39
	v_fmac_f32_e32 v33, v10, v40
	v_fmac_f32_e32 v42, v12, v38
	v_add_f32_e32 v33, v33, v42
	s_nop 1
	v_add_f32_dpp v33, v33, v33 quad_perm:[1,0,3,2] row_mask:0xf bank_mask:0xf bound_ctrl:1
	s_nop 1
	v_add_f32_dpp v33, v33, v33 quad_perm:[2,3,0,1] row_mask:0xf bank_mask:0xf bound_ctrl:1
	s_nop 1
	v_add_f32_dpp v33, v33, v33 row_half_mirror row_mask:0xf bank_mask:0xf bound_ctrl:1
	s_nop 1
	v_mov_b32_dpp v42, v33 row_mirror row_mask:0xf bank_mask:0xf bound_ctrl:1
	s_and_saveexec_b64 s[0:1], s[8:9]
	v_add_f32_e32 v33, v33, v42
	v_cndmask_b32_e64 v33, v229, v33, s[12:13]
	ds_write_b32 v27, v33 offset:512
	s_or_b64 exec, exec, s[0:1]
	v_mul_f32_e32 v33, v7, v41
	v_mul_f32_e32 v42, v9, v39
	v_fmac_f32_e32 v33, v6, v40
	v_fmac_f32_e32 v42, v8, v38
	v_add_f32_e32 v33, v33, v42
	s_nop 1
	v_add_f32_dpp v33, v33, v33 quad_perm:[1,0,3,2] row_mask:0xf bank_mask:0xf bound_ctrl:1
	s_nop 1
	v_add_f32_dpp v33, v33, v33 quad_perm:[2,3,0,1] row_mask:0xf bank_mask:0xf bound_ctrl:1
	s_nop 1
	v_add_f32_dpp v33, v33, v33 row_half_mirror row_mask:0xf bank_mask:0xf bound_ctrl:1
	s_nop 1
	v_mov_b32_dpp v42, v33 row_mirror row_mask:0xf bank_mask:0xf bound_ctrl:1
	s_and_saveexec_b64 s[0:1], s[8:9]
	v_add_f32_e32 v33, v33, v42
	v_cndmask_b32_e64 v33, v229, v33, s[12:13]
	ds_write_b32 v27, v33 offset:1024
	s_or_b64 exec, exec, s[0:1]
	v_mul_f32_e32 v33, v3, v41
	v_mul_f32_e32 v39, v5, v39
	v_fmac_f32_e32 v33, v2, v40
	v_fmac_f32_e32 v39, v4, v38
	v_add_f32_e32 v33, v33, v39
	s_nop 1
	v_add_f32_dpp v33, v33, v33 quad_perm:[1,0,3,2] row_mask:0xf bank_mask:0xf bound_ctrl:1
	s_nop 1
	v_add_f32_dpp v33, v33, v33 quad_perm:[2,3,0,1] row_mask:0xf bank_mask:0xf bound_ctrl:1
	s_nop 1
	v_add_f32_dpp v33, v33, v33 row_half_mirror row_mask:0xf bank_mask:0xf bound_ctrl:1
	s_nop 1
	v_mov_b32_dpp v38, v33 row_mirror row_mask:0xf bank_mask:0xf bound_ctrl:1
	s_and_saveexec_b64 s[0:1], s[8:9]
	v_add_f32_e32 v33, v33, v38
	v_cndmask_b32_e64 v33, v229, v33, s[12:13]
	ds_write_b32 v27, v33 offset:1536
	s_or_b64 exec, exec, s[0:1]
	v_or_b32_e32 v27, 8, v15
	v_cmp_gt_i32_e64 s[16:17], s34, v27
	s_nop 1
	v_cndmask_b32_e64 v38, v228, v27, s[16:17]
	v_ashrrev_i32_e32 v39, 31, v38
	v_lshlrev_b64 v[40:41], 10, v[38:39]
	v_lshl_add_u64 v[44:45], v[52:53], 0, v[40:41]
	v_lshl_add_u64 v[42:43], v[40:41], 0, s[78:79]
	v_lshl_add_u64 v[50:51], v[52:53], 0, v[42:43]
	v_lshl_add_u32 v27, v27, 2, s35
	s_waitcnt vmcnt(2)
	v_mov_b64 v[44:45], v[88:89]
	v_mov_b64 v[46:47], v[90:91]
	v_mov_b64 v[58:59], v[92:93]
	v_mov_b64 v[60:61], v[94:95]
	v_pk_add_f32 v[46:47], v[46:47], v[60:61]
	v_pk_add_f32 v[50:51], v[44:45], v[58:59]
	v_pk_add_f32 v[44:45], v[24:25], v[46:47]
	v_pk_add_f32 v[46:47], v[22:23], v[50:51]
	v_mul_f32_e32 v39, v21, v45
	v_mul_f32_e32 v33, v19, v47
	v_fmac_f32_e32 v33, v18, v46
	v_fmac_f32_e32 v39, v20, v44
	v_add_f32_e32 v33, v33, v39
	s_nop 1
	v_add_f32_dpp v33, v33, v33 quad_perm:[1,0,3,2] row_mask:0xf bank_mask:0xf bound_ctrl:1
	s_nop 1
	v_add_f32_dpp v33, v33, v33 quad_perm:[2,3,0,1] row_mask:0xf bank_mask:0xf bound_ctrl:1
	s_nop 1
	v_add_f32_dpp v33, v33, v33 row_half_mirror row_mask:0xf bank_mask:0xf bound_ctrl:1
	s_nop 1
	v_mov_b32_dpp v39, v33 row_mirror row_mask:0xf bank_mask:0xf bound_ctrl:1
	s_and_saveexec_b64 s[0:1], s[8:9]
	v_add_f32_e32 v33, v33, v39
	v_cndmask_b32_e64 v33, v229, v33, s[16:17]
	ds_write_b32 v27, v33
	s_or_b64 exec, exec, s[0:1]
	v_mul_f32_e32 v33, v11, v47
	v_mul_f32_e32 v39, v13, v45
	v_fmac_f32_e32 v33, v10, v46
	v_fmac_f32_e32 v39, v12, v44
	v_add_f32_e32 v33, v33, v39
	s_nop 1
	v_add_f32_dpp v33, v33, v33 quad_perm:[1,0,3,2] row_mask:0xf bank_mask:0xf bound_ctrl:1
	s_nop 1
	v_add_f32_dpp v33, v33, v33 quad_perm:[2,3,0,1] row_mask:0xf bank_mask:0xf bound_ctrl:1
	s_nop 1
	v_add_f32_dpp v33, v33, v33 row_half_mirror row_mask:0xf bank_mask:0xf bound_ctrl:1
	s_nop 1
	v_mov_b32_dpp v39, v33 row_mirror row_mask:0xf bank_mask:0xf bound_ctrl:1
	s_and_saveexec_b64 s[0:1], s[8:9]
	v_add_f32_e32 v33, v33, v39
	v_cndmask_b32_e64 v33, v229, v33, s[16:17]
	ds_write_b32 v27, v33 offset:512
	s_or_b64 exec, exec, s[0:1]
	v_mul_f32_e32 v33, v7, v47
	v_mul_f32_e32 v39, v9, v45
	v_fmac_f32_e32 v33, v6, v46
	v_fmac_f32_e32 v39, v8, v44
	v_add_f32_e32 v33, v33, v39
	s_nop 1
	v_add_f32_dpp v33, v33, v33 quad_perm:[1,0,3,2] row_mask:0xf bank_mask:0xf bound_ctrl:1
	s_nop 1
	v_add_f32_dpp v33, v33, v33 quad_perm:[2,3,0,1] row_mask:0xf bank_mask:0xf bound_ctrl:1
	s_nop 1
	v_add_f32_dpp v33, v33, v33 row_half_mirror row_mask:0xf bank_mask:0xf bound_ctrl:1
	s_nop 1
	v_mov_b32_dpp v39, v33 row_mirror row_mask:0xf bank_mask:0xf bound_ctrl:1
	s_and_saveexec_b64 s[0:1], s[8:9]
	v_add_f32_e32 v33, v33, v39
	v_cndmask_b32_e64 v33, v229, v33, s[16:17]
	ds_write_b32 v27, v33 offset:1024
	s_or_b64 exec, exec, s[0:1]
	v_mul_f32_e32 v33, v3, v47
	v_mul_f32_e32 v39, v5, v45
	v_fmac_f32_e32 v33, v2, v46
	v_fmac_f32_e32 v39, v4, v44
	v_add_f32_e32 v33, v33, v39
	s_nop 1
	v_add_f32_dpp v33, v33, v33 quad_perm:[1,0,3,2] row_mask:0xf bank_mask:0xf bound_ctrl:1
	s_nop 1
	v_add_f32_dpp v33, v33, v33 quad_perm:[2,3,0,1] row_mask:0xf bank_mask:0xf bound_ctrl:1
	s_nop 1
	v_add_f32_dpp v33, v33, v33 row_half_mirror row_mask:0xf bank_mask:0xf bound_ctrl:1
	s_nop 1
	v_mov_b32_dpp v39, v33 row_mirror row_mask:0xf bank_mask:0xf bound_ctrl:1
	s_and_saveexec_b64 s[0:1], s[8:9]
	v_add_f32_e32 v33, v33, v39
	v_cndmask_b32_e64 v33, v229, v33, s[16:17]
	ds_write_b32 v27, v33 offset:1536
	s_or_b64 exec, exec, s[0:1]
	v_or_b32_e32 v15, 12, v15
	v_cmp_gt_i32_e64 s[18:19], s34, v15
	s_nop 1
	v_cndmask_b32_e64 v44, v228, v15, s[18:19]
	v_ashrrev_i32_e32 v45, 31, v44
	v_lshlrev_b64 v[46:47], 10, v[44:45]
	v_lshl_add_u64 v[58:59], v[52:53], 0, v[46:47]
	v_lshl_add_u64 v[50:51], v[46:47], 0, s[78:79]
	v_lshl_add_u64 v[52:53], v[52:53], 0, v[50:51]
	v_lshl_add_u32 v15, v15, 2, s35
	s_waitcnt vmcnt(0)
; #define LAS __attribute__((address_space(3)))
; __device__ __forceinline__ float wave_sum(float v) { v = sum16(v); v += lane_xor<16>(v); return xhalf_sum(v); }
; __device__ __forceinline__ float wave_max(float v) { v = max16(v); v = fmaxf(v, lane_xor<16>(v)); return xhalf_max(v); }
; __device__ __forceinline__ float dot4(f32x4 a, f32x4 b) { return (a[0] * b[0] + a[1] * b[1]) + (a[2] * b[2] + a[3] * b[3]); }
; __device__ __forceinline__ float grp16_sum(float v) { return sum16(v); }
; __device__ __forceinline__ void attn_sample_item(const SmpArgs& a, int b, int g, LAS unsigned char* lds, int tid) {
;     ...
;       for (int it = 0; it < 4; ++it) { const int c = 16 * w + 4 * it + kq; const int cc = c < 127 ? c : 126;
;           const f32x4 kx = *(const f32x4*)(pqk + (size_t)cc * 256) + *(const f32x4*)(pqk + (size_t)(cc + 1) * 256 + 64) + cbk;
; #pragma unroll
;           for (int h = 0; h < 4; ++h) { const float s = grp16_sum(dot4(kx, qv[h])); if (d4 == 0) sc[h * 128 + c] = c < 127 ? s : -1e30f; } } }
;     __syncthreads();
;     if (w < 4) { LAS float* r = sc + w * 128; const float v0 = r[lane], v1 = r[lane + 64]; const float mx = wave_max(fmaxf(v0, v1));
;         const float p0 = v0 > -1e29f ? __builtin_amdgcn_exp2f(v0 - mx) : 0.f, p1 = v1 > -1e29f ? __builtin_amdgcn_exp2f(v1 - mx) : 0.f;
;         const float s = wave_sum(p0 + p1); const float inv = s > 0.f ? 1.0f / s : 0.f; r[lane] = p0 * inv; r[lane + 64] = p1 * inv; }
	v_mov_b64 v[58:59], v[96:97]
	v_mov_b64 v[60:61], v[98:99]
	v_mov_b64 v[62:63], v[100:101]
	v_mov_b64 v[64:65], v[102:103]
	v_pk_add_f32 v[52:53], v[60:61], v[64:65]
	v_pk_add_f32 v[58:59], v[58:59], v[62:63]
	v_pk_add_f32 v[24:25], v[24:25], v[52:53]
	v_pk_add_f32 v[22:23], v[22:23], v[58:59]
	v_mul_f32_e32 v21, v21, v25
	v_mul_f32_e32 v19, v19, v23
	v_fmac_f32_e32 v19, v18, v22
	v_fmac_f32_e32 v21, v20, v24
	v_add_f32_e32 v18, v19, v21
	s_nop 1
	v_add_f32_dpp v18, v18, v18 quad_perm:[1,0,3,2] row_mask:0xf bank_mask:0xf bound_ctrl:1
	s_nop 1
	v_add_f32_dpp v18, v18, v18 quad_perm:[2,3,0,1] row_mask:0xf bank_mask:0xf bound_ctrl:1
	s_nop 1
	v_add_f32_dpp v18, v18, v18 row_half_mirror row_mask:0xf bank_mask:0xf bound_ctrl:1
	s_nop 1
	v_mov_b32_dpp v19, v18 row_mirror row_mask:0xf bank_mask:0xf bound_ctrl:1
	s_and_saveexec_b64 s[0:1], s[8:9]
	v_add_f32_e32 v18, v18, v19
	v_cndmask_b32_e64 v18, v229, v18, s[18:19]
	ds_write_b32 v15, v18
	s_or_b64 exec, exec, s[0:1]
	v_mul_f32_e32 v11, v11, v23
	v_fmac_f32_e32 v11, v10, v22
	v_mul_f32_e32 v10, v13, v25
	v_fmac_f32_e32 v10, v12, v24
	v_add_f32_e32 v10, v11, v10
	s_nop 1
	v_add_f32_dpp v10, v10, v10 quad_perm:[1,0,3,2] row_mask:0xf bank_mask:0xf bound_ctrl:1
	s_nop 1
	v_add_f32_dpp v10, v10, v10 quad_perm:[2,3,0,1] row_mask:0xf bank_mask:0xf bound_ctrl:1
	s_nop 1
	v_add_f32_dpp v10, v10, v10 row_half_mirror row_mask:0xf bank_mask:0xf bound_ctrl:1
	s_nop 1
	v_mov_b32_dpp v11, v10 row_mirror row_mask:0xf bank_mask:0xf bound_ctrl:1
	s_and_saveexec_b64 s[0:1], s[8:9]
	v_add_f32_e32 v10, v10, v11
	v_cndmask_b32_e64 v10, v229, v10, s[18:19]
	ds_write_b32 v15, v10 offset:512
	s_or_b64 exec, exec, s[0:1]
	v_mul_f32_e32 v7, v7, v23
	v_fmac_f32_e32 v7, v6, v22
	v_mul_f32_e32 v6, v9, v25
	v_fmac_f32_e32 v6, v8, v24
	v_add_f32_e32 v6, v7, v6
	s_nop 1
	v_add_f32_dpp v6, v6, v6 quad_perm:[1,0,3,2] row_mask:0xf bank_mask:0xf bound_ctrl:1
	s_nop 1
	v_add_f32_dpp v6, v6, v6 quad_perm:[2,3,0,1] row_mask:0xf bank_mask:0xf bound_ctrl:1
	s_nop 1
	v_add_f32_dpp v6, v6, v6 row_half_mirror row_mask:0xf bank_mask:0xf bound_ctrl:1
	s_nop 1
	v_mov_b32_dpp v7, v6 row_mirror row_mask:0xf bank_mask:0xf bound_ctrl:1
	s_and_saveexec_b64 s[0:1], s[8:9]
	v_add_f32_e32 v6, v6, v7
	v_cndmask_b32_e64 v6, v229, v6, s[18:19]
	ds_write_b32 v15, v6 offset:1024
	s_or_b64 exec, exec, s[0:1]
	v_mul_f32_e32 v3, v3, v23
	v_fmac_f32_e32 v3, v2, v22
	v_mul_f32_e32 v2, v5, v25
	v_fmac_f32_e32 v2, v4, v24
	v_add_f32_e32 v2, v3, v2
	s_nop 1
	v_add_f32_dpp v2, v2, v2 quad_perm:[1,0,3,2] row_mask:0xf bank_mask:0xf bound_ctrl:1
	s_nop 1
	v_add_f32_dpp v2, v2, v2 quad_perm:[2,3,0,1] row_mask:0xf bank_mask:0xf bound_ctrl:1
	s_nop 1
	v_add_f32_dpp v2, v2, v2 row_half_mirror row_mask:0xf bank_mask:0xf bound_ctrl:1
	s_nop 1
	v_mov_b32_dpp v3, v2 row_mirror row_mask:0xf bank_mask:0xf bound_ctrl:1
	s_and_saveexec_b64 s[0:1], s[8:9]
	v_add_f32_e32 v2, v2, v3
	v_cndmask_b32_e64 v2, v229, v2, s[18:19]
	ds_write_b32 v15, v2 offset:1536
	s_or_b64 exec, exec, s[0:1]
	v_cmp_gt_i32_e32 vcc, 4, v49
	v_lshlrev_b32_e32 v45, 2, v17
	s_waitcnt lgkmcnt(0)
	s_barrier
	s_and_saveexec_b64 s[0:1], vcc
	s_cbranch_execz .LBB0_2542
	v_lshlrev_b32_e32 v2, 9, v49
	v_add3_u32 v4, s35, v2, v45
	ds_read2st64_b32 v[2:3], v4 offset1:1
	s_waitcnt lgkmcnt(0)
	v_max_f32_e32 v5, v3, v3
	v_max_f32_e32 v6, v2, v2
	v_max_f32_e32 v5, v6, v5
	v_cmp_lt_f32_e32 vcc, s2, v2
	s_nop 0
	v_mov_b32_dpp v6, v5 quad_perm:[1,0,3,2] row_mask:0xf bank_mask:0xf bound_ctrl:1
	v_max_f32_e32 v6, v6, v6
	v_max_f32_e32 v5, v5, v6
	s_nop 1
	v_mov_b32_dpp v6, v5 quad_perm:[2,3,0,1] row_mask:0xf bank_mask:0xf bound_ctrl:1
	v_max_f32_e32 v6, v6, v6
	v_max_f32_e32 v5, v5, v6
	s_nop 1
	v_mov_b32_dpp v6, v5 row_half_mirror row_mask:0xf bank_mask:0xf bound_ctrl:1
	v_max_f32_e32 v6, v6, v6
	v_max_f32_e32 v5, v5, v6
	s_nop 1
	v_mov_b32_dpp v6, v5 row_mirror row_mask:0xf bank_mask:0xf bound_ctrl:1
	v_max_f32_e32 v6, v6, v6
	v_max_f32_e32 v5, v5, v6
	ds_swizzle_b32 v6, v5 offset:swizzle(SWAP,16)
	s_waitcnt lgkmcnt(0)
	v_max_f32_e32 v6, v6, v6
	v_max_f32_e32 v5, v5, v6
	v_mov_b32_e32 v6, v5
	s_nop 1
	v_permlane32_swap_b32_e32 v5, v6
	v_max_f32_e32 v6, v6, v6
	v_max_f32_e32 v5, v5, v5
	v_max_f32_e32 v5, v5, v6
	v_sub_f32_e32 v6, v2, v5
	v_exp_f32_e32 v6, v6
	v_sub_f32_e32 v5, v3, v5
	v_exp_f32_e32 v5, v5
	v_cndmask_b32_e32 v2, 0, v6, vcc
	v_cmp_lt_f32_e32 vcc, s2, v3
	s_nop 1
	v_cndmask_b32_e32 v3, 0, v5, vcc
	v_add_f32_e32 v5, v2, v3
	s_nop 1
	v_add_f32_dpp v5, v5, v5 quad_perm:[1,0,3,2] row_mask:0xf bank_mask:0xf bound_ctrl:1
	s_nop 1
	v_add_f32_dpp v5, v5, v5 quad_perm:[2,3,0,1] row_mask:0xf bank_mask:0xf bound_ctrl:1
	s_nop 1
	v_add_f32_dpp v5, v5, v5 row_half_mirror row_mask:0xf bank_mask:0xf bound_ctrl:1
	s_nop 1
	v_add_f32_dpp v5, v5, v5 row_mirror row_mask:0xf bank_mask:0xf bound_ctrl:1
	ds_swizzle_b32 v6, v5 offset:swizzle(SWAP,16)
	s_waitcnt lgkmcnt(0)
	v_add_f32_e32 v5, v5, v6
	v_mov_b32_e32 v6, v5
	s_nop 1
	v_permlane32_swap_b32_e32 v5, v6
	v_add_f32_e32 v5, v5, v6
	v_div_scale_f32 v6, s[20:21], v5, v5, 1.0
	v_rcp_f32_e32 v7, v6
	v_div_scale_f32 v8, vcc, 1.0, v5, 1.0
	v_fma_f32 v9, -v6, v7, 1.0
	v_fmac_f32_e32 v7, v9, v7
	v_mul_f32_e32 v9, v8, v7
	v_fma_f32 v10, -v6, v9, v8
	v_fmac_f32_e32 v9, v10, v7
	v_fma_f32 v6, -v6, v9, v8
	v_div_fmas_f32 v6, v6, v7, v9
	v_div_fixup_f32 v6, v6, v5, 1.0
	v_cmp_lt_f32_e32 vcc, 0, v5
	s_nop 1
	v_cndmask_b32_e32 v5, 0, v6, vcc
	v_mul_f32_e32 v2, v2, v5
	v_mul_f32_e32 v3, v3, v5
	ds_write2st64_b32 v4, v2, v3 offset1:1
